# attention xor-32 shuffles: ds_bpermute replaced by v_permlane32_swap + cndmask
# speedup vs baseline: 1.0026x; 1.0006x over previous
; __device__ __forceinline__ void attn_phase(LAS unsigned char* lds, const bf16_t* Q, const bf16_t* Kp, const bf16_t* Vp, bf16_t* O, int first, int stride, int end, int wave, int lane) {
;     ...
;             f32x16 p = {};
; #pragma unroll
;             for (int d0 = 0; d0 < 4; ++d0) p = __builtin_amdgcn_mfma_f32_32x32x16_bf16(kc[d0], qr[d0], p, 0, 0, 0);
;             const bool diag = (kt == qblk);
;             float beta[16], om[16];
; #pragma unroll
;             for (int r = 0; r < 16; ++r) {
;                 const float z = p[r] * 0.125f, e = __builtin_amdgcn_exp2f(-LOG2E * __builtin_fabsf(z)), rc = __builtin_amdgcn_rcpf(1.f + e), sm = e * rc;
;                 const bool pos = z >= 0.f; float bt = pos ? rc : sm, o_ = pos ? sm : rc;
;                 const int kvl = (r & 3) + 8 * (r >> 2) + 4 * hi;
;                 if (diag && kvl >= r32) { bt = 0.f; o_ = 1.f; }
;                 beta[r] = bt; om[r] = o_;
;             }
;             float Gm[4], Gp[4];
; #pragma unroll
;             for (int g = 0; g < 4; ++g) { Gm[g] = (om[4 * g] * om[4 * g + 1]) * (om[4 * g + 2] * om[4 * g + 3]); Gp[g] = __shfl_xor(Gm[g], 32); }
;             float SO[4], SP[4];
;             SO[3] = 1.f; SO[2] = Gm[3]; SO[1] = SO[2] * Gm[2]; SO[0] = SO[1] * Gm[1];
;             SP[3] = 1.f; SP[2] = Gp[3]; SP[1] = SP[2] * Gp[2]; SP[0] = SP[1] * Gp[1];
;             float A[16];
; #pragma unroll
;             for (int g = 0; g < 4; ++g) {
;                 const float E = carry * SO[g] * (hi ? SP[g] : SP[g] * Gp[g]);
;                 const float P3 = E, P2 = P3 * om[4 * g + 3], P1 = P2 * om[4 * g + 2], P0 = P1 * om[4 * g + 1];
;                 A[4 * g + 3] = beta[4 * g + 3] * P3; A[4 * g + 2] = beta[4 * g + 2] * P2; A[4 * g + 1] = beta[4 * g + 1] * P1; A[4 * g] = beta[4 * g] * P0;
;             }
.LBB0_104:
	s_or_b64 exec, exec, s[4:5]
	s_waitcnt lgkmcnt(3)
	v_mfma_f32_32x32x16_bf16 v[0:15], v[0:3], v[48:51], 0
	s_waitcnt lgkmcnt(2)
	v_mfma_f32_32x32x16_bf16 v[0:15], v[24:27], v[52:55], v[0:15]
	s_waitcnt lgkmcnt(1)
	v_mfma_f32_32x32x16_bf16 v[0:15], v[20:23], v[56:59], v[0:15]
	s_waitcnt lgkmcnt(0)
	v_mfma_f32_32x32x16_bf16 v[0:15], v[16:19], v[60:63], v[0:15]
	s_nop 11
	v_mul_f32_e32 v0, 0x3e000000, v0
	v_mul_f32_e32 v1, 0x3e000000, v1
	v_mul_f32_e64 v16, |v0|, s8
	v_mul_f32_e32 v2, 0x3e000000, v2
	v_mul_f32_e64 v17, |v1|, s8
	v_exp_f32_e32 v16, v16
	v_mul_f32_e64 v18, |v2|, s8
	v_exp_f32_e32 v17, v17
	v_exp_f32_e32 v18, v18
	v_mul_f32_e32 v3, 0x3e000000, v3
	v_add_f32_e32 v20, 1.0, v16
	v_mul_f32_e64 v19, |v3|, s8
	v_add_f32_e32 v21, 1.0, v17
	v_rcp_f32_e32 v20, v20
	v_exp_f32_e32 v19, v19
	v_add_f32_e32 v22, 1.0, v18
	v_rcp_f32_e32 v21, v21
	v_rcp_f32_e32 v22, v22
	v_mul_f32_e32 v16, v16, v20
	v_cmp_le_f32_e32 vcc, 0, v0
	v_add_f32_e32 v23, 1.0, v19
	v_mul_f32_e32 v17, v17, v21
	v_cndmask_b32_e32 v0, v20, v16, vcc
	v_cndmask_b32_e32 v16, v16, v20, vcc
	v_cmp_le_f32_e32 vcc, 0, v1
	v_mul_f32_e32 v4, 0x3e000000, v4
	v_rcp_f32_e32 v23, v23
	v_mul_f32_e32 v18, v18, v22
	v_cndmask_b32_e32 v1, v21, v17, vcc
	v_cndmask_b32_e32 v17, v17, v21, vcc
	v_cmp_le_f32_e32 vcc, 0, v2
	v_mul_f32_e32 v5, 0x3e000000, v5
	v_cndmask_b32_e64 v21, 0, v16, s[42:43]
	v_cndmask_b32_e32 v2, v22, v18, vcc
	v_cndmask_b32_e32 v18, v18, v22, vcc
	v_cmp_le_f32_e32 vcc, 0, v3
	v_cndmask_b32_e64 v3, 1.0, v0, s[42:43]
	v_mul_f32_e64 v0, |v4|, s8
	v_exp_f32_e32 v0, v0
	v_mul_f32_e64 v16, |v5|, s8
	v_mul_f32_e32 v19, v19, v23
	v_exp_f32_e32 v16, v16
	v_cndmask_b32_e64 v24, 1.0, v2, s[46:47]
	v_cndmask_b32_e32 v2, v19, v23, vcc
	v_cndmask_b32_e32 v20, v23, v19, vcc
	v_cndmask_b32_e64 v23, 0, v2, s[48:49]
	v_add_f32_e32 v2, 1.0, v0
	v_rcp_f32_e32 v2, v2
	v_cndmask_b32_e64 v22, 0, v17, s[44:45]
	v_add_f32_e32 v17, 1.0, v16
	v_rcp_f32_e32 v17, v17
	v_mul_f32_e32 v0, v0, v2
	v_cmp_le_f32_e32 vcc, 0, v4
	v_cndmask_b32_e64 v25, 0, v18, s[46:47]
	v_cndmask_b32_e64 v1, 1.0, v1, s[44:45]
	v_cndmask_b32_e32 v4, v2, v0, vcc
	v_cndmask_b32_e32 v0, v0, v2, vcc
	v_cndmask_b32_e64 v26, 0, v0, s[50:51]
	v_mul_f32_e32 v0, v16, v17
	v_cmp_le_f32_e32 vcc, 0, v5
	v_mul_f32_e32 v5, 0x3e000000, v6
	v_mul_f32_e64 v6, |v5|, s8
	v_cndmask_b32_e32 v2, v17, v0, vcc
	v_exp_f32_e32 v16, v6
	v_cndmask_b32_e64 v6, 1.0, v2, s[52:53]
	v_mul_f32_e32 v2, 0x3e000000, v7
	v_mul_f32_e64 v7, |v2|, s8
	v_exp_f32_e32 v7, v7
	v_cndmask_b32_e32 v0, v0, v17, vcc
	v_cndmask_b32_e64 v27, 0, v0, s[52:53]
	v_add_f32_e32 v0, 1.0, v16
	v_rcp_f32_e32 v0, v0
	v_add_f32_e32 v17, 1.0, v7
	v_rcp_f32_e32 v17, v17
	v_cmp_le_f32_e32 vcc, 0, v5
	v_mul_f32_e32 v16, v16, v0
	v_cndmask_b32_e64 v4, 1.0, v4, s[50:51]
	v_cndmask_b32_e32 v5, v0, v16, vcc
	v_cndmask_b32_e32 v0, v16, v0, vcc
	v_cndmask_b32_e64 v16, 1.0, v5, s[54:55]
	v_cndmask_b32_e64 v28, 0, v0, s[54:55]
	v_mul_f32_e32 v0, v7, v17
	v_cmp_le_f32_e32 vcc, 0, v2
	v_mul_f32_e32 v5, 0x3e000000, v8
	v_mul_f32_e64 v7, |v5|, s8
	v_cndmask_b32_e32 v2, v17, v0, vcc
	v_exp_f32_e32 v7, v7
	v_cndmask_b32_e64 v8, 1.0, v2, s[56:57]
	v_mul_f32_e32 v2, 0x3e000000, v9
	v_mul_f32_e64 v9, |v2|, s8
	v_exp_f32_e32 v9, v9
	v_cndmask_b32_e32 v0, v0, v17, vcc
	v_cndmask_b32_e64 v29, 0, v0, s[56:57]
	v_add_f32_e32 v0, 1.0, v7
	v_rcp_f32_e32 v0, v0
	v_add_f32_e32 v17, 1.0, v9
	v_rcp_f32_e32 v17, v17
	v_cmp_le_f32_e32 vcc, 0, v5
	v_mul_f32_e32 v7, v7, v0
	v_cndmask_b32_e64 v20, 1.0, v20, s[48:49]
	v_cndmask_b32_e32 v5, v0, v7, vcc
	v_cndmask_b32_e32 v0, v7, v0, vcc
	v_cndmask_b32_e64 v30, 0, v0, s[58:59]
	v_mul_f32_e32 v0, v9, v17
	v_cmp_le_f32_e32 vcc, 0, v2
	v_mul_f32_e32 v7, 0x3e000000, v10
	v_mul_f32_e64 v9, |v7|, s8
	v_cndmask_b32_e32 v2, v17, v0, vcc
	v_exp_f32_e32 v9, v9
	v_cndmask_b32_e64 v31, 1.0, v2, s[60:61]
	v_mul_f32_e32 v2, 0x3e000000, v11
	v_mul_f32_e64 v10, |v2|, s8
	v_exp_f32_e32 v10, v10
	v_cndmask_b32_e32 v0, v0, v17, vcc
	v_cndmask_b32_e64 v34, 0, v0, s[60:61]
	v_add_f32_e32 v0, 1.0, v9
	v_rcp_f32_e32 v0, v0
	v_add_f32_e32 v11, 1.0, v10
	v_rcp_f32_e32 v11, v11
	v_cmp_le_f32_e32 vcc, 0, v7
	v_mul_f32_e32 v9, v9, v0
	v_cndmask_b32_e64 v5, 1.0, v5, s[58:59]
	v_cndmask_b32_e32 v7, v0, v9, vcc
	v_cndmask_b32_e32 v0, v9, v0, vcc
	v_cndmask_b32_e64 v35, 1.0, v7, s[62:63]
	v_cndmask_b32_e64 v36, 0, v0, s[62:63]
	v_mul_f32_e32 v0, v10, v11
	v_cmp_le_f32_e32 vcc, 0, v2
	v_mul_f32_e32 v7, 0x3e000000, v12
	v_mul_f32_e64 v9, |v7|, s8
	v_cndmask_b32_e32 v2, v11, v0, vcc
	v_exp_f32_e32 v9, v9
	v_cndmask_b32_e64 v37, 1.0, v2, s[64:65]
	v_mul_f32_e32 v2, 0x3e000000, v13
	v_mul_f32_e64 v10, |v2|, s8
	v_exp_f32_e32 v10, v10
	v_cndmask_b32_e32 v0, v0, v11, vcc
	v_cndmask_b32_e64 v38, 0, v0, s[64:65]
	v_add_f32_e32 v0, 1.0, v9
	v_rcp_f32_e32 v0, v0
	v_add_f32_e32 v11, 1.0, v10
	v_rcp_f32_e32 v11, v11
	v_cmp_le_f32_e32 vcc, 0, v7
	v_mul_f32_e32 v9, v9, v0
	v_mul_f32_e32 v17, v5, v31
	v_cndmask_b32_e32 v7, v0, v9, vcc
	v_cndmask_b32_e32 v0, v9, v0, vcc
	v_cndmask_b32_e64 v19, 0, v0, s[66:67]
	v_mul_f32_e32 v0, v10, v11
	v_cmp_le_f32_e32 vcc, 0, v2
	v_mul_f32_e32 v9, 0x3e000000, v14
	v_mul_f32_e64 v10, |v9|, s8
	v_cndmask_b32_e32 v2, v11, v0, vcc
	v_exp_f32_e32 v10, v10
	v_cndmask_b32_e64 v18, 1.0, v2, s[68:69]
	v_mul_f32_e32 v2, 0x3e000000, v15
	v_cndmask_b32_e32 v0, v0, v11, vcc
	v_mul_f32_e64 v11, |v2|, s8
	v_exp_f32_e32 v11, v11
	v_cndmask_b32_e64 v39, 0, v0, s[68:69]
	v_add_f32_e32 v0, 1.0, v10
	v_rcp_f32_e32 v0, v0
	v_add_f32_e32 v12, 1.0, v11
	v_rcp_f32_e32 v12, v12
	v_cmp_le_f32_e32 vcc, 0, v9
	v_mul_f32_e32 v10, v10, v0
	v_cndmask_b32_e64 v7, 1.0, v7, s[66:67]
	v_cndmask_b32_e32 v9, v0, v10, vcc
	v_cndmask_b32_e32 v0, v10, v0, vcc
	v_cndmask_b32_e64 v41, 0, v0, s[70:71]
	v_mul_f32_e32 v0, v11, v12
	v_cmp_le_f32_e32 vcc, 0, v2
	v_cndmask_b32_e64 v40, 1.0, v9, s[70:71]
	v_mul_f32_e32 v5, v7, v18
	v_cndmask_b32_e32 v2, v12, v0, vcc
	v_cndmask_b32_e64 v42, 1.0, v2, s[72:73]
	v_mul_f32_e32 v7, v40, v42
	v_cndmask_b32_e32 v0, v0, v12, vcc
	v_mul_f32_e32 v9, v35, v37
	v_pk_mul_f32 v[4:5], v[4:5], v[6:7]
	v_cndmask_b32_e64 v43, 0, v0, s[72:73]
	v_pk_mul_f32 v[12:13], v[16:17], v[8:9]
	v_mov_b32_e32 v0, v5
	v_mov_b32_e32 v160, v5
	s_nop 1
	v_permlane32_swap_b32_e32 v0, v160
	v_cndmask_b32_e64 v0, v0, v160, s[40:41]
	v_pk_mul_f32 v[14:15], v[4:5], v[12:13]
	v_mov_b32_e32 v2, v13
	v_mov_b32_e32 v160, v13
	s_nop 1
	v_permlane32_swap_b32_e32 v2, v160
	v_cndmask_b32_e64 v2, v2, v160, s[40:41]
	v_mov_b32_e32 v10, v14
	v_mov_b32_e32 v160, v14
	s_nop 1
	v_permlane32_swap_b32_e32 v10, v160
	v_cndmask_b32_e64 v10, v10, v160, s[40:41]
	v_mul_f32_e32 v11, v24, v20
	s_waitcnt lgkmcnt(2)
; __device__ __forceinline__ void attn_phase(LAS unsigned char* lds, const bf16_t* Q, const bf16_t* Kp, const bf16_t* Vp, bf16_t* O, int first, int stride, int end, int wave, int lane) {
;     ...
;             for (int g = 0; g < 4; ++g) { Gm[g] = (om[4 * g] * om[4 * g + 1]) * (om[4 * g + 2] * om[4 * g + 3]); Gp[g] = __shfl_xor(Gm[g], 32); }
;             float SO[4], SP[4];
;             SO[3] = 1.f; SO[2] = Gm[3]; SO[1] = SO[2] * Gm[2]; SO[0] = SO[1] * Gm[1];
;             SP[3] = 1.f; SP[2] = Gp[3]; SP[1] = SP[2] * Gp[2]; SP[0] = SP[1] * Gp[1];
;             float A[16];
; #pragma unroll
;             for (int g = 0; g < 4; ++g) {
;                 const float E = carry * SO[g] * (hi ? SP[g] : SP[g] * Gp[g]);
;                 const float P3 = E, P2 = P3 * om[4 * g + 3], P1 = P2 * om[4 * g + 2], P0 = P1 * om[4 * g + 1];
;                 A[4 * g + 3] = beta[4 * g + 3] * P3; A[4 * g + 2] = beta[4 * g + 2] * P2; A[4 * g + 1] = beta[4 * g + 1] * P1; A[4 * g] = beta[4 * g] * P0;
;             }
;             carry = carry * (SO[0] * Gm[0]) * (SP[0] * Gp[0]);
;             u32x4 pw0, pw1;
;             pw0.x = cvt_pk_bf16(A[0], A[1]); pw0.y = cvt_pk_bf16(A[2], A[3]); pw0.z = cvt_pk_bf16(A[4], A[5]); pw0.w = cvt_pk_bf16(A[6], A[7]);
;             pw1.x = cvt_pk_bf16(A[8], A[9]); pw1.y = cvt_pk_bf16(A[10], A[11]); pw1.z = cvt_pk_bf16(A[12], A[13]); pw1.w = cvt_pk_bf16(A[14], A[15]);
;             const bf16x8 pa0 = __builtin_bit_cast(bf16x8, pw0), pa1 = __builtin_bit_cast(bf16x8, pw1);
;             asm volatile("s_waitcnt lgkmcnt(0)" ::: "memory");
; #pragma unroll
;             for (int s = 0; s < 2; ++s)
; #pragma unroll
;                 for (int d0 = 0; d0 < 2; ++d0) {
;                     const v4i16_t lo = __builtin_amdgcn_ds_read_tr16_b64_v4i16((LAS v4i16_t*)(vl + trb + s * 2048 + d0 * 64));
;                     const v4i16_t hh = __builtin_amdgcn_ds_read_tr16_b64_v4i16((LAS v4i16_t*)(vl + trb + s * 2048 + 1024 + d0 * 64));
;                     const bf16x8 vf = (bf16x8){lo[0], lo[1], lo[2], lo[3], hh[0], hh[1], hh[2], hh[3]};
;                     if (d0 == 0) o0 = __builtin_amdgcn_mfma_f32_32x32x16_bf16(s ? pa1 : pa0, vf, o0, 0, 0, 0);
;                     else         o1 = __builtin_amdgcn_mfma_f32_32x32x16_bf16(s ? pa1 : pa0, vf, o1, 0, 0, 0);
;                 }
;             asm volatile("s_waitcnt lgkmcnt(0)" ::: "memory");
	v_cndmask_b32_e64 v4, 1.0, v0, s[40:41]
	v_mul_f32_e32 v7, v4, v42
	s_waitcnt lgkmcnt(1)
	v_pk_mul_f32 v[2:3], v[2:3], v[0:1]
	v_pk_mul_f32 v[12:13], v[14:15], v[14:15] op_sel:[0,1] op_sel_hi:[1,0]
	v_mul_f32_e32 v9, v40, v7
	s_waitcnt lgkmcnt(0)
	v_pk_mul_f32 v[10:11], v[2:3], v[10:11]
	v_mul_f32_e32 v13, v18, v9
	v_mov_b32_e32 v18, v11
	v_mov_b32_e32 v160, v11
	s_nop 1
	v_permlane32_swap_b32_e32 v18, v160
	v_cndmask_b32_e64 v18, v18, v160, s[40:41]
	v_mul_f32_e32 v3, v41, v7
	v_mul_f32_e32 v7, v39, v9
	v_mul_f32_e32 v9, v19, v13
	v_mov_b32_e32 v19, v12
	s_waitcnt lgkmcnt(0)
	v_pk_mul_f32 v[46:47], v[10:11], v[18:19]
	v_cndmask_b32_e64 v0, v0, v2, s[40:41]
	v_cndmask_b32_e64 v11, v10, v46, s[40:41]
	v_cndmask_b32_e64 v10, v2, v10, s[40:41]
	v_mul_f32_e32 v11, v11, v12
	v_mul_f32_e32 v10, v10, v15
	v_mul_f32_e32 v0, v0, v5
	v_mul_f32_e32 v12, v20, v11
	v_mul_f32_e32 v8, v8, v10
	v_mul_f32_e32 v2, v37, v0
	v_mul_f32_e32 v13, v24, v12
	v_mul_f32_e32 v14, v16, v8
	v_mul_f32_e32 v5, v35, v2
	v_mul_f32_e32 v1, v1, v13
	v_mul_f32_e32 v6, v6, v14
	v_mul_f32_e32 v15, v31, v5
	v_mul_f32_e32 v4, v4, v43
	v_mul_f32_e32 v11, v23, v11
	v_mul_f32_e32 v12, v25, v12
	v_mul_f32_e32 v13, v22, v13
	v_mul_f32_e32 v1, v21, v1
	v_mul_f32_e32 v10, v29, v10
	v_mul_f32_e32 v8, v28, v8
	v_mul_f32_e32 v14, v27, v14
	v_mul_f32_e32 v6, v26, v6
	v_mul_f32_e32 v0, v38, v0
	v_mul_f32_e32 v2, v36, v2
	v_mul_f32_e32 v5, v34, v5
	v_mul_f32_e32 v15, v30, v15
	v_cvt_pk_bf16_f32 v16, v1, v13
	v_cvt_pk_bf16_f32 v17, v12, v11
	v_cvt_pk_bf16_f32 v18, v6, v14
	v_cvt_pk_bf16_f32 v19, v8, v10
	v_cvt_pk_bf16_f32 v34, v15, v5
	v_cvt_pk_bf16_f32 v35, v2, v0
	v_cvt_pk_bf16_f32 v36, v9, v7
	v_cvt_pk_bf16_f32 v37, v3, v4
	s_waitcnt lgkmcnt(0)
	ds_read_b64_tr_b16 v[0:1], v144
	ds_read_b64_tr_b16 v[2:3], v144 offset:1024
	ds_read_b64_tr_b16 v[22:23], v144 offset:1088
	ds_read_b64_tr_b16 v[20:21], v144 offset:64
	s_waitcnt lgkmcnt(2)
	v_mfma_f32_32x32x16_bf16 v[0:15], v[16:19], v[0:3], 0
	ds_read_b64_tr_b16 v[38:39], v144 offset:2048
	ds_read_b64_tr_b16 v[40:41], v144 offset:3072
	ds_read_b64_tr_b16 v[44:45], v144 offset:3136
	ds_read_b64_tr_b16 v[42:43], v144 offset:2112
	v_mul_f32_e32 v133, v46, v47
	v_cmp_lt_f32_e32 vcc, s13, v133
	s_waitcnt lgkmcnt(0)
	s_cmp_lg_u64 vcc, 0
	s_cselect_b64 s[4:5], -1, 0
	v_cmp_ne_u32_e32 vcc, 0, v121
	s_waitcnt lgkmcnt(4)
	v_mfma_f32_32x32x16_bf16 v[16:31], v[16:19], v[20:23], 0
	s_and_b64 s[4:5], vcc, s[4:5]
	s_waitcnt lgkmcnt(2)
	v_mfma_f32_32x32x16_bf16 v[0:15], v[34:37], v[38:41], v[0:15]
	s_waitcnt lgkmcnt(0)
	v_mfma_f32_32x32x16_bf16 v[16:31], v[34:37], v[42:45], v[16:31]
	s_and_saveexec_b64 s[34:35], s[4:5]
	s_cbranch_execz .LBB0_101
	s_movk_i32 s2, 0x7f
	v_and_b32_sdwa v176, v137, s2 dst_sel:WORD_1 dst_unused:UNUSED_PAD src0_sel:DWORD src1_sel:DWORD
	v_lshlrev_b64 v[32:33], 23, v[32:33]
	s_movk_i32 s2, 0x780
	v_and_or_b32 v32, v138, s2, v32
	v_lshl_add_u64 v[128:129], v[112:113], 0, v[32:33]
	v_lshl_add_u64 v[130:131], v[114:115], 0, v[32:33]
	s_mov_b64 s[4:5], 0x10000
	s_mov_b64 s[36:37], 0
	s_branch .LBB0_107
.LBB0_106:
	s_or_b64 exec, exec, s[74:75]
	s_waitcnt lgkmcnt(3)
	v_mfma_f32_32x32x16_bf16 v[32:47], v[32:35], v[48:51], 0
	v_lshl_add_u64 v[128:129], v[128:129], 0, s[10:11]
	v_lshl_add_u64 v[130:131], v[130:131], 0, s[10:11]
	s_waitcnt lgkmcnt(2)
	v_mfma_f32_32x32x16_bf16 v[32:47], v[104:107], v[52:55], v[32:47]
	s_waitcnt lgkmcnt(1)
	v_mfma_f32_32x32x16_bf16 v[32:47], v[100:103], v[56:59], v[32:47]
	s_waitcnt lgkmcnt(0)
	v_mfma_f32_32x32x16_bf16 v[32:47], v[96:99], v[60:63], v[32:47]
	s_nop 11
	v_mov_b32_e32 v96, v32
	v_mov_b32_e32 v97, v34
	v_mov_b32_e32 v34, v33
	v_pk_mul_f32 v[96:97], v[96:97], s[12:13] op_sel_hi:[1,0]
	v_pk_mul_f32 v[34:35], v[34:35], s[12:13] op_sel_hi:[1,0]
	v_mov_b32_e32 v32, v36
	v_mov_b32_e32 v33, v38
	v_mul_f32_e64 v36, |v96|, s8
	v_mul_f32_e64 v38, |v97|, s8
	v_mul_f32_e64 v100, |v34|, s8
	v_mul_f32_e64 v101, |v35|, s8
	v_exp_f32_e32 v98, v36
	v_exp_f32_e32 v99, v38
	v_exp_f32_e32 v100, v100
	v_exp_f32_e32 v101, v101
	v_add_f32_e32 v36, 1.0, v98
	v_add_f32_e32 v38, 1.0, v99
	v_add_f32_e32 v104, 1.0, v100
	v_add_f32_e32 v105, 1.0, v101
	v_rcp_f32_e32 v102, v36
	v_rcp_f32_e32 v103, v38
	v_rcp_f32_e32 v104, v104
	v_rcp_f32_e32 v105, v105
	v_pk_mul_f32 v[32:33], v[32:33], s[12:13] op_sel_hi:[1,0]
	v_mov_b32_e32 v38, v37
	v_mul_f32_e64 v106, |v32|, s8
	v_mul_f32_e64 v107, |v33|, s8
	v_exp_f32_e32 v106, v106
	v_exp_f32_e32 v107, v107
	v_pk_mul_f32 v[38:39], v[38:39], s[12:13] op_sel_hi:[1,0]
	v_pk_mul_f32 v[98:99], v[98:99], v[102:103]
	v_pk_mul_f32 v[100:101], v[100:101], v[104:105]
	v_cmp_le_f32_e32 vcc, 0, v96
	v_cmp_le_f32_e64 s[74:75], 0, v34
	v_mul_f32_e64 v37, |v38|, s8
	v_cndmask_b32_e32 v119, v98, v102, vcc
	v_cndmask_b32_e64 v123, v100, v104, s[74:75]
	v_cmp_le_f32_e64 s[76:77], 0, v97
	v_cndmask_b32_e32 v96, v102, v98, vcc
	v_cmp_le_f32_e32 vcc, 0, v35
	v_cndmask_b32_e64 v34, v104, v100, s[74:75]
	v_exp_f32_e32 v100, v37
	v_mul_f32_e64 v37, |v39|, s8
	v_cndmask_b32_e64 v97, v103, v99, s[76:77]
	v_cndmask_b32_e32 v145, v101, v105, vcc
	v_cndmask_b32_e32 v35, v105, v101, vcc
	v_exp_f32_e32 v101, v37
	v_cndmask_b32_e64 v127, v99, v103, s[76:77]
	v_pk_mul_f32 v[98:99], v[96:97], v[34:35]
	v_add_f32_e32 v36, 1.0, v106
	v_add_f32_e32 v96, 1.0, v107
	v_rcp_f32_e32 v36, v36
	v_rcp_f32_e32 v37, v96
	v_add_f32_e32 v96, 1.0, v100
	v_rcp_f32_e32 v102, v96
	v_add_f32_e32 v96, 1.0, v101
	v_rcp_f32_e32 v103, v96
	v_pk_mul_f32 v[104:105], v[106:107], v[36:37]
	v_cmp_le_f32_e32 vcc, 0, v32
	v_cmp_le_f32_e64 s[74:75], 0, v38
	v_mov_b32_e32 v38, v40
	v_cndmask_b32_e32 v96, v104, v36, vcc
	v_cndmask_b32_e32 v32, v36, v104, vcc
; __device__ __forceinline__ void attn_phase(LAS unsigned char* lds, const bf16_t* Q, const bf16_t* Kp, const bf16_t* Vp, bf16_t* O, int first, int stride, int end, int wave, int lane) {
;     ...
;             float beta[16], om[16];
; #pragma unroll
;             for (int r = 0; r < 16; ++r) {
;                 const float z = p[r] * 0.125f, e = __builtin_amdgcn_exp2f(-LOG2E * __builtin_fabsf(z)), rc = __builtin_amdgcn_rcpf(1.f + e), sm = e * rc;
;                 const bool pos = z >= 0.f; float bt = pos ? rc : sm, o_ = pos ? sm : rc;
;                 const int kvl = (r & 3) + 8 * (r >> 2) + 4 * hi;
;                 if (diag && kvl >= r32) { bt = 0.f; o_ = 1.f; }
;                 beta[r] = bt; om[r] = o_;
;             }
;             float Gm[4], Gp[4];
; #pragma unroll
;             for (int g = 0; g < 4; ++g) { Gm[g] = (om[4 * g] * om[4 * g + 1]) * (om[4 * g + 2] * om[4 * g + 3]); Gp[g] = __shfl_xor(Gm[g], 32); }
;             float SO[4], SP[4];
;             SO[3] = 1.f; SO[2] = Gm[3]; SO[1] = SO[2] * Gm[2]; SO[0] = SO[1] * Gm[1];
;             SP[3] = 1.f; SP[2] = Gp[3]; SP[1] = SP[2] * Gp[2]; SP[0] = SP[1] * Gp[1];
;             float A[16];
; #pragma unroll
;             for (int g = 0; g < 4; ++g) {
;                 const float E = carry * SO[g] * (hi ? SP[g] : SP[g] * Gp[g]);
;                 const float P3 = E, P2 = P3 * om[4 * g + 3], P1 = P2 * om[4 * g + 2], P0 = P1 * om[4 * g + 1];
;                 A[4 * g + 3] = beta[4 * g + 3] * P3; A[4 * g + 2] = beta[4 * g + 2] * P2; A[4 * g + 1] = beta[4 * g + 1] * P1; A[4 * g] = beta[4 * g] * P0;
;             }
;             carry = carry * (SO[0] * Gm[0]) * (SP[0] * Gp[0]);
;             u32x4 pw0, pw1;
;             pw0.x = cvt_pk_bf16(A[0], A[1]); pw0.y = cvt_pk_bf16(A[2], A[3]); pw0.z = cvt_pk_bf16(A[4], A[5]); pw0.w = cvt_pk_bf16(A[6], A[7]);
;             pw1.x = cvt_pk_bf16(A[8], A[9]); pw1.y = cvt_pk_bf16(A[10], A[11]); pw1.z = cvt_pk_bf16(A[12], A[13]); pw1.w = cvt_pk_bf16(A[14], A[15]);
;             const bf16x8 pa0 = __builtin_bit_cast(bf16x8, pw0), pa1 = __builtin_bit_cast(bf16x8, pw1);
;             asm volatile("s_waitcnt lgkmcnt(0)" ::: "memory");
; #pragma unroll
;             for (int s = 0; s < 2; ++s)
; #pragma unroll
;                 for (int d0 = 0; d0 < 2; ++d0) {
	v_cmp_le_f32_e32 vcc, 0, v39
	v_mov_b32_e32 v39, v42
	v_pk_mul_f32 v[38:39], v[38:39], s[12:13] op_sel_hi:[1,0]
	v_pk_mul_f32 v[100:101], v[100:101], v[102:103]
	v_mul_f32_e64 v40, |v38|, s8
	v_cndmask_b32_e64 v148, v100, v102, s[74:75]
	v_cmp_le_f32_e64 s[76:77], 0, v33
	v_cndmask_b32_e64 v36, v102, v100, s[74:75]
	v_exp_f32_e32 v100, v40
	v_mul_f32_e64 v40, |v39|, s8
	v_cndmask_b32_e64 v149, v105, v37, s[76:77]
	v_cndmask_b32_e64 v33, v37, v105, s[76:77]
	v_cndmask_b32_e32 v150, v101, v103, vcc
	v_cndmask_b32_e32 v37, v103, v101, vcc
	v_exp_f32_e32 v101, v40
	v_mov_b32_e32 v42, v41
	v_pk_mul_f32 v[42:43], v[42:43], s[12:13] op_sel_hi:[1,0]
	v_pk_mul_f32 v[102:103], v[32:33], v[36:37]
	v_add_f32_e32 v32, 1.0, v100
	v_mul_f32_e64 v41, |v42|, s8
	v_rcp_f32_e32 v40, v32
	v_add_f32_e32 v32, 1.0, v101
	v_exp_f32_e32 v104, v41
	v_mul_f32_e64 v41, |v43|, s8
	v_exp_f32_e32 v105, v41
	v_rcp_f32_e32 v41, v32
	v_add_f32_e32 v32, 1.0, v104
	v_rcp_f32_e32 v106, v32
	v_add_f32_e32 v32, 1.0, v105
	v_pk_mul_f32 v[100:101], v[100:101], v[40:41]
	v_cmp_le_f32_e32 vcc, 0, v38
	v_rcp_f32_e32 v107, v32
	v_cmp_le_f32_e64 s[74:75], 0, v42
	v_cndmask_b32_e32 v32, v100, v40, vcc
	v_cndmask_b32_e32 v38, v40, v100, vcc
	v_cmp_le_f32_e32 vcc, 0, v43
	v_mov_b32_e32 v42, v44
	v_mov_b32_e32 v43, v46
	v_pk_mul_f32 v[42:43], v[42:43], s[12:13] op_sel_hi:[1,0]
	v_mov_b32_e32 v46, v45
	v_mul_f32_e64 v44, |v42|, s8
	v_cmp_le_f32_e64 s[76:77], 0, v39
	v_exp_f32_e32 v100, v44
	v_mul_f32_e64 v44, |v43|, s8
	v_pk_mul_f32 v[46:47], v[46:47], s[12:13] op_sel_hi:[1,0]
	v_pk_mul_f32 v[104:105], v[104:105], v[106:107]
	v_cndmask_b32_e64 v152, v101, v41, s[76:77]
	v_cndmask_b32_e64 v39, v41, v101, s[76:77]
	v_exp_f32_e32 v101, v44
	v_mul_f32_e64 v45, |v46|, s8
	v_cndmask_b32_e64 v151, v104, v106, s[74:75]
	v_cndmask_b32_e64 v40, v106, v104, s[74:75]
	v_exp_f32_e32 v106, v45
	v_mul_f32_e64 v45, |v47|, s8
	v_cndmask_b32_e32 v153, v105, v107, vcc
	v_cndmask_b32_e32 v41, v107, v105, vcc
	v_exp_f32_e32 v107, v45
	v_pk_mul_f32 v[104:105], v[38:39], v[40:41]
	v_add_f32_e32 v38, 1.0, v100
	v_rcp_f32_e32 v44, v38
	v_add_f32_e32 v38, 1.0, v101
	v_rcp_f32_e32 v45, v38
	v_add_f32_e32 v38, 1.0, v106
	v_rcp_f32_e32 v146, v38
	v_add_f32_e32 v38, 1.0, v107
	v_rcp_f32_e32 v147, v38
	v_pk_mul_f32 v[100:101], v[100:101], v[44:45]
	v_cmp_le_f32_e32 vcc, 0, v42
	v_cmp_le_f32_e64 s[74:75], 0, v46
	v_pk_mul_f32 v[106:107], v[106:107], v[146:147]
	v_cndmask_b32_e32 v38, v100, v44, vcc
	v_cmp_le_f32_e64 s[76:77], 0, v43
	v_cndmask_b32_e32 v42, v44, v100, vcc
	v_cmp_le_f32_e32 vcc, 0, v47
	v_cndmask_b32_e64 v132, v101, v45, s[76:77]
	v_cndmask_b32_e64 v43, v45, v101, s[76:77]
	v_cndmask_b32_e32 v45, v147, v107, vcc
	v_cndmask_b32_e64 v44, v146, v106, s[74:75]
	v_pk_mul_f32 v[46:47], v[42:43], v[44:45]
	v_mov_b32_e32 v101, v104
	v_mov_b32_e32 v100, v46
	v_mov_b32_e32 v104, v47
	v_pk_mul_f32 v[46:47], v[100:101], v[104:105]
	v_mov_b32_e32 v100, v46
	v_mov_b32_e32 v160, v46
	s_nop 1
	v_permlane32_swap_b32_e32 v100, v160
	v_cndmask_b32_e64 v100, v100, v160, s[40:41]
	v_mov_b32_e32 v42, v47
	v_mov_b32_e32 v160, v47
	s_nop 1
	v_permlane32_swap_b32_e32 v42, v160
	v_cndmask_b32_e64 v42, v42, v160, s[40:41]
	v_mov_b32_e32 v104, v102
	v_mov_b32_e32 v105, v46
	v_mov_b32_e32 v102, v103
	v_mov_b32_e32 v103, v47
	s_waitcnt lgkmcnt(1)
	v_cndmask_b32_e64 v101, 1.0, v100, s[40:41]
	v_pk_mul_f32 v[102:103], v[104:105], v[102:103]
	v_mul_f32_e32 v101, v133, v101
	v_cndmask_b32_e64 v154, v106, v146, s[74:75]
	v_cndmask_b32_e32 v155, v107, v147, vcc
	v_pk_mul_f32 v[106:107], v[102:103], v[102:103] op_sel:[0,1] op_sel_hi:[1,0]
	v_mul_f32_e32 v45, v101, v45
	v_mov_b32_e32 v104, v102
	v_mov_b32_e32 v160, v102
	s_nop 1
	v_permlane32_swap_b32_e32 v104, v160
	v_cndmask_b32_e64 v104, v104, v160, s[40:41]
	v_mul_f32_e32 v102, v133, v103
	v_mul_f32_e32 v103, v43, v45
	v_mul_f32_e32 v107, v101, v155
	v_mov_b32_e32 v43, v98
	v_mov_b32_e32 v101, v99
	s_waitcnt lgkmcnt(1)
	v_pk_mul_f32 v[42:43], v[42:43], v[100:101]
	v_mul_f32_e32 v146, v132, v45
	v_mov_b32_e32 v132, v43
	v_mov_b32_e32 v160, v43
	s_nop 1
	v_permlane32_swap_b32_e32 v132, v160
	v_cndmask_b32_e64 v132, v132, v160, s[40:41]
	v_mul_f32_e32 v44, v44, v103
	v_mov_b32_e32 v105, v106
	v_mul_f32_e32 v38, v38, v44
	s_waitcnt lgkmcnt(1)
	v_pk_mul_f32 v[44:45], v[42:43], v[104:105]
	v_mul_f32_e32 v47, v133, v106
	s_waitcnt lgkmcnt(0)
	v_pk_mul_f32 v[98:99], v[44:45], v[132:133]
	v_mul_f32_e32 v46, v133, v46
	v_cndmask_b32_e64 v43, v44, v98, s[40:41]
	v_cndmask_b32_e64 v44, v42, v44, s[40:41]
	v_mul_f32_e32 v44, v44, v102
	v_mul_f32_e32 v37, v37, v44
	v_mul_f32_e32 v33, v33, v37
	v_mul_f32_e32 v43, v43, v47
	v_mul_f32_e32 v36, v36, v33
	v_mul_f32_e32 v47, v148, v33
	v_cndmask_b32_e64 v33, v100, v42, s[40:41]
	v_mul_f32_e32 v35, v35, v43
	v_mul_f32_e32 v33, v33, v46
	v_mul_f32_e32 v45, v97, v35
	v_mul_f32_e32 v41, v41, v33
	v_mul_f32_e32 v34, v34, v45
	v_mul_f32_e32 v39, v39, v41
	v_mul_f32_e32 v35, v127, v35
	v_mul_f32_e32 v34, v119, v34
	v_mul_f32_e32 v37, v149, v37
	v_mul_f32_e32 v36, v96, v36
	v_mul_f32_e32 v40, v40, v39
	v_mul_f32_e32 v39, v151, v39
	v_mul_f32_e32 v101, v154, v103
	v_mul_f32_e32 v43, v145, v43
	v_mul_f32_e32 v45, v123, v45
	v_mul_f32_e32 v44, v150, v44
	v_mul_f32_e32 v42, v153, v33
	v_mul_f32_e32 v41, v152, v41
	v_mul_f32_e32 v40, v32, v40
	v_cvt_pk_bf16_f32 v32, v34, v45
	v_cvt_pk_bf16_f32 v33, v35, v43
	v_cvt_pk_bf16_f32 v34, v36, v47
	v_cvt_pk_bf16_f32 v35, v37, v44
	v_cvt_pk_bf16_f32 v36, v40, v39
	v_cvt_pk_bf16_f32 v37, v41, v42
	v_cvt_pk_bf16_f32 v38, v38, v101
	v_cvt_pk_bf16_f32 v39, v146, v107
	s_waitcnt lgkmcnt(0)
	ds_read_b64_tr_b16 v[40:41], v144
	ds_read_b64_tr_b16 v[42:43], v144 offset:1024
	ds_read_b64_tr_b16 v[46:47], v144 offset:1088
	ds_read_b64_tr_b16 v[44:45], v144 offset:64
	s_waitcnt lgkmcnt(2)
	v_mfma_f32_32x32x16_bf16 v[0:15], v[32:35], v[40:43], v[0:15]
	v_mul_f32_e32 v133, v98, v99
	v_cmp_lt_f32_e32 vcc, s13, v133
	s_cmp_eq_u64 vcc, 0
	s_cselect_b64 s[74:75], -1, 0
	v_cmp_gt_u32_e32 vcc, 2, v121
	s_or_b64 s[74:75], vcc, s[74:75]
	s_add_u32 s4, s4, 0x10000
	s_waitcnt lgkmcnt(0)
	v_mfma_f32_32x32x16_bf16 v[16:31], v[32:35], v[44:47], v[16:31]
	ds_read_b64_tr_b16 v[32:33], v144 offset:2048
	ds_read_b64_tr_b16 v[34:35], v144 offset:3072
	ds_read_b64_tr_b16 v[42:43], v144 offset:3136
	ds_read_b64_tr_b16 v[40:41], v144 offset:2112
	s_waitcnt lgkmcnt(0)
	s_addc_u32 s5, s5, 0
	s_and_b64 s[74:75], exec, s[74:75]
	s_or_b64 s[36:37], s[74:75], s[36:37]
	v_add_u32_e32 v121, -1, v121
	s_waitcnt lgkmcnt(2)
	v_mfma_f32_32x32x16_bf16 v[0:15], v[36:39], v[32:35], v[0:15]
	s_waitcnt lgkmcnt(0)
	v_mfma_f32_32x32x16_bf16 v[16:31], v[36:39], v[40:43], v[16:31]
	s_andn2_b64 exec, exec, s[36:37]
	s_cbranch_execz .LBB0_100
